# ctx mini-GEMM K loop: six k-steps of fragments requested per wait instead of two dependent round trips per k-step
# speedup vs baseline: 1.0020x; 1.0020x over previous
.LBB0_736:
	s_sub_i32 s99, s36, s35
	s_min_i32 s99, s99, 6
	s_mov_b32 s19, s81
	s_mov_b32 s29, s81
	s_ashr_i32 s13, s12, 31
	s_lshl_b64 s[38:39], s[12:13], 1
	v_lshl_add_u64 v[54:55], v[46:47], 0, s[38:39]
	v_lshl_add_u64 v[56:57], v[48:49], 0, s[38:39]
	global_load_dwordx4 v[76:79], v[54:55], off
	global_load_dwordx4 v[84:87], v[56:57], off
	v_lshl_add_u64 v[58:59], v[56:57], 0, s[80:81]
	v_lshl_add_u64 v[60:61], v[56:57], 0, s[18:19]
	v_lshl_add_u64 v[62:63], v[56:57], 0, s[28:29]
	v_lshl_add_u64 v[64:65], v[54:55], 0, s[80:81]
	global_load_dwordx4 v[88:91], v[58:59], off
	global_load_dwordx4 v[92:95], v[60:61], off
	global_load_dwordx4 v[96:99], v[62:63], off
	global_load_dwordx4 v[80:83], v[64:65], off
	s_add_i32 s12, s12, 32
	s_cmp_le_i32 s99, 1
	s_cbranch_scc1 .Lp1_issued
	s_ashr_i32 s13, s12, 31
	s_lshl_b64 s[38:39], s[12:13], 1
	v_lshl_add_u64 v[54:55], v[46:47], 0, s[38:39]
	v_lshl_add_u64 v[56:57], v[48:49], 0, s[38:39]
	global_load_dwordx4 v[100:103], v[54:55], off
	global_load_dwordx4 v[108:111], v[56:57], off
	v_lshl_add_u64 v[58:59], v[56:57], 0, s[80:81]
	v_lshl_add_u64 v[60:61], v[56:57], 0, s[18:19]
	v_lshl_add_u64 v[62:63], v[56:57], 0, s[28:29]
	v_lshl_add_u64 v[64:65], v[54:55], 0, s[80:81]
	global_load_dwordx4 v[112:115], v[58:59], off
	global_load_dwordx4 v[116:119], v[60:61], off
	global_load_dwordx4 v[120:123], v[62:63], off
	global_load_dwordx4 v[104:107], v[64:65], off
	s_add_i32 s12, s12, 32
	s_cmp_le_i32 s99, 2
	s_cbranch_scc1 .Lp1_issued
	s_ashr_i32 s13, s12, 31
	s_lshl_b64 s[38:39], s[12:13], 1
	v_lshl_add_u64 v[54:55], v[46:47], 0, s[38:39]
	v_lshl_add_u64 v[56:57], v[48:49], 0, s[38:39]
	global_load_dwordx4 v[124:127], v[54:55], off
	global_load_dwordx4 v[132:135], v[56:57], off
	v_lshl_add_u64 v[58:59], v[56:57], 0, s[80:81]
	v_lshl_add_u64 v[60:61], v[56:57], 0, s[18:19]
	v_lshl_add_u64 v[62:63], v[56:57], 0, s[28:29]
	v_lshl_add_u64 v[64:65], v[54:55], 0, s[80:81]
	global_load_dwordx4 v[136:139], v[58:59], off
	global_load_dwordx4 v[140:143], v[60:61], off
	global_load_dwordx4 v[148:151], v[62:63], off
	global_load_dwordx4 v[128:131], v[64:65], off
	s_add_i32 s12, s12, 32
	s_cmp_le_i32 s99, 3
	s_cbranch_scc1 .Lp1_issued
	s_ashr_i32 s13, s12, 31
	s_lshl_b64 s[38:39], s[12:13], 1
	v_lshl_add_u64 v[54:55], v[46:47], 0, s[38:39]
	v_lshl_add_u64 v[56:57], v[48:49], 0, s[38:39]
	global_load_dwordx4 v[152:155], v[54:55], off
	global_load_dwordx4 v[160:163], v[56:57], off
	v_lshl_add_u64 v[58:59], v[56:57], 0, s[80:81]
	v_lshl_add_u64 v[60:61], v[56:57], 0, s[18:19]
	v_lshl_add_u64 v[62:63], v[56:57], 0, s[28:29]
	v_lshl_add_u64 v[64:65], v[54:55], 0, s[80:81]
	global_load_dwordx4 v[164:167], v[58:59], off
	global_load_dwordx4 v[168:171], v[60:61], off
	global_load_dwordx4 v[172:175], v[62:63], off
	global_load_dwordx4 v[156:159], v[64:65], off
	s_add_i32 s12, s12, 32
	s_cmp_le_i32 s99, 4
	s_cbranch_scc1 .Lp1_issued
	s_ashr_i32 s13, s12, 31
	s_lshl_b64 s[38:39], s[12:13], 1
	v_lshl_add_u64 v[54:55], v[46:47], 0, s[38:39]
	v_lshl_add_u64 v[56:57], v[48:49], 0, s[38:39]
	global_load_dwordx4 v[176:179], v[54:55], off
	global_load_dwordx4 v[184:187], v[56:57], off
	v_lshl_add_u64 v[58:59], v[56:57], 0, s[80:81]
	v_lshl_add_u64 v[60:61], v[56:57], 0, s[18:19]
	v_lshl_add_u64 v[62:63], v[56:57], 0, s[28:29]
	v_lshl_add_u64 v[64:65], v[54:55], 0, s[80:81]
	global_load_dwordx4 v[188:191], v[58:59], off
	global_load_dwordx4 v[192:195], v[60:61], off
	global_load_dwordx4 v[196:199], v[62:63], off
	global_load_dwordx4 v[180:183], v[64:65], off
	s_add_i32 s12, s12, 32
	s_cmp_le_i32 s99, 5
	s_cbranch_scc1 .Lp1_issued
	s_ashr_i32 s13, s12, 31
	s_lshl_b64 s[38:39], s[12:13], 1
	v_lshl_add_u64 v[54:55], v[46:47], 0, s[38:39]
	v_lshl_add_u64 v[56:57], v[48:49], 0, s[38:39]
	global_load_dwordx4 v[200:203], v[54:55], off
	global_load_dwordx4 v[208:211], v[56:57], off
	v_lshl_add_u64 v[58:59], v[56:57], 0, s[80:81]
	v_lshl_add_u64 v[60:61], v[56:57], 0, s[18:19]
	v_lshl_add_u64 v[62:63], v[56:57], 0, s[28:29]
	v_lshl_add_u64 v[64:65], v[54:55], 0, s[80:81]
	global_load_dwordx4 v[212:215], v[58:59], off
	global_load_dwordx4 v[220:223], v[60:61], off
	global_load_dwordx4 v[224:227], v[62:63], off
	global_load_dwordx4 v[204:207], v[64:65], off
	s_add_i32 s12, s12, 32
.Lp1_issued:
	s_waitcnt vmcnt(0)
	v_mfma_f32_16x16x32_bf16 v[34:37], v[76:79], v[84:87], v[34:37]
	v_mfma_f32_16x16x32_bf16 v[38:41], v[76:79], v[88:91], v[38:41]
	v_mfma_f32_16x16x32_bf16 v[30:33], v[76:79], v[92:95], v[30:33]
	v_mfma_f32_16x16x32_bf16 v[26:29], v[76:79], v[96:99], v[26:29]
	v_mfma_f32_16x16x32_bf16 v[22:25], v[80:83], v[84:87], v[22:25]
	v_mfma_f32_16x16x32_bf16 v[18:21], v[80:83], v[88:91], v[18:21]
	v_mfma_f32_16x16x32_bf16 v[14:17], v[80:83], v[92:95], v[14:17]
	v_mfma_f32_16x16x32_bf16 v[10:13], v[80:83], v[96:99], v[10:13]
	s_cmp_le_i32 s99, 1
	s_cbranch_scc1 .Lp1_done
	v_mfma_f32_16x16x32_bf16 v[34:37], v[100:103], v[108:111], v[34:37]
	v_mfma_f32_16x16x32_bf16 v[38:41], v[100:103], v[112:115], v[38:41]
	v_mfma_f32_16x16x32_bf16 v[30:33], v[100:103], v[116:119], v[30:33]
	v_mfma_f32_16x16x32_bf16 v[26:29], v[100:103], v[120:123], v[26:29]
	v_mfma_f32_16x16x32_bf16 v[22:25], v[104:107], v[108:111], v[22:25]
	v_mfma_f32_16x16x32_bf16 v[18:21], v[104:107], v[112:115], v[18:21]
	v_mfma_f32_16x16x32_bf16 v[14:17], v[104:107], v[116:119], v[14:17]
	v_mfma_f32_16x16x32_bf16 v[10:13], v[104:107], v[120:123], v[10:13]
	s_cmp_le_i32 s99, 2
	s_cbranch_scc1 .Lp1_done
	v_mfma_f32_16x16x32_bf16 v[34:37], v[124:127], v[132:135], v[34:37]
	v_mfma_f32_16x16x32_bf16 v[38:41], v[124:127], v[136:139], v[38:41]
	v_mfma_f32_16x16x32_bf16 v[30:33], v[124:127], v[140:143], v[30:33]
	v_mfma_f32_16x16x32_bf16 v[26:29], v[124:127], v[148:151], v[26:29]
	v_mfma_f32_16x16x32_bf16 v[22:25], v[128:131], v[132:135], v[22:25]
	v_mfma_f32_16x16x32_bf16 v[18:21], v[128:131], v[136:139], v[18:21]
	v_mfma_f32_16x16x32_bf16 v[14:17], v[128:131], v[140:143], v[14:17]
	v_mfma_f32_16x16x32_bf16 v[10:13], v[128:131], v[148:151], v[10:13]
	s_cmp_le_i32 s99, 3
	s_cbranch_scc1 .Lp1_done
	v_mfma_f32_16x16x32_bf16 v[34:37], v[152:155], v[160:163], v[34:37]
	v_mfma_f32_16x16x32_bf16 v[38:41], v[152:155], v[164:167], v[38:41]
	v_mfma_f32_16x16x32_bf16 v[30:33], v[152:155], v[168:171], v[30:33]
	v_mfma_f32_16x16x32_bf16 v[26:29], v[152:155], v[172:175], v[26:29]
	v_mfma_f32_16x16x32_bf16 v[22:25], v[156:159], v[160:163], v[22:25]
	v_mfma_f32_16x16x32_bf16 v[18:21], v[156:159], v[164:167], v[18:21]
	v_mfma_f32_16x16x32_bf16 v[14:17], v[156:159], v[168:171], v[14:17]
	v_mfma_f32_16x16x32_bf16 v[10:13], v[156:159], v[172:175], v[10:13]
	s_cmp_le_i32 s99, 4
	s_cbranch_scc1 .Lp1_done
	v_mfma_f32_16x16x32_bf16 v[34:37], v[176:179], v[184:187], v[34:37]
	v_mfma_f32_16x16x32_bf16 v[38:41], v[176:179], v[188:191], v[38:41]
	v_mfma_f32_16x16x32_bf16 v[30:33], v[176:179], v[192:195], v[30:33]
	v_mfma_f32_16x16x32_bf16 v[26:29], v[176:179], v[196:199], v[26:29]
	v_mfma_f32_16x16x32_bf16 v[22:25], v[180:183], v[184:187], v[22:25]
	v_mfma_f32_16x16x32_bf16 v[18:21], v[180:183], v[188:191], v[18:21]
	v_mfma_f32_16x16x32_bf16 v[14:17], v[180:183], v[192:195], v[14:17]
	v_mfma_f32_16x16x32_bf16 v[10:13], v[180:183], v[196:199], v[10:13]
	s_cmp_le_i32 s99, 5
	s_cbranch_scc1 .Lp1_done
	v_mfma_f32_16x16x32_bf16 v[34:37], v[200:203], v[208:211], v[34:37]
	v_mfma_f32_16x16x32_bf16 v[38:41], v[200:203], v[212:215], v[38:41]
	v_mfma_f32_16x16x32_bf16 v[30:33], v[200:203], v[220:223], v[30:33]
	v_mfma_f32_16x16x32_bf16 v[26:29], v[200:203], v[224:227], v[26:29]
	v_mfma_f32_16x16x32_bf16 v[22:25], v[204:207], v[208:211], v[22:25]
	v_mfma_f32_16x16x32_bf16 v[18:21], v[204:207], v[212:215], v[18:21]
	v_mfma_f32_16x16x32_bf16 v[14:17], v[204:207], v[220:223], v[14:17]
	v_mfma_f32_16x16x32_bf16 v[10:13], v[204:207], v[224:227], v[10:13]
.Lp1_done:
	s_add_i32 s35, s35, s99
	s_cmp_lt_i32 s35, s36
	s_cbranch_scc1 .LBB0_736
	s_mov_b32 s38, 0x63000
	s_mov_b32 s39, 0xc6000
